# conv: each XCD sweeps its own eighth of the token range from the end (rows its up-proj workgroups wrote last) instead of one global sweep
# baseline (speedup 1.0000x reference)
; __device__ __forceinline__ int opaque_tid() { int t = threadIdx.x; asm volatile("" : "+v"(t)); return t; }
; __device__ void phase_conv(const Params& p, int l, int nrows) {
;     bf16_t* Aup = (bf16_t*)(p.ws + WS_BIG); const bf16_t* Gup = Aup + (size_t)NROW * FF;
;     const float* cw = p.in[18] + (size_t)l * 9 * FF; const float* cb = p.in[19] + (size_t)l * FF;
;     const int tid_ = opaque_tid();
;     const long total = (long)(nrows / 16) * 352;
;     for (long id0 = (long)blockIdx.x * 512 + tid_; id0 < total; id0 += (long)gridDim.x * 512) {
;         const int seg = (int)((total - 1 - id0) / 352), f0 = (int)(id0 % 352) * 8;
.LBB0_699:
	s_or_b64 exec, exec, s[0:1]
	s_lshr_b32 s0, s85, 4
	s_waitcnt lgkmcnt(0)
	v_mov_b32_e32 v0, v135
	s_mul_i32 s38, s0, 0x160
	v_readlane_b32 s0, v242, 56
	s_barrier
	v_readlane_b32 s1, v242, 57
	v_readlane_b32 s32, v242, 58
	s_mov_b32 s19, s38
	s_cmp_lg_u32 s46, 0x100
	s_cbranch_scc1 .Lcv_keep
	s_bitcmp1_b32 s38, 0
	s_cbranch_scc1 .Lcv_keep
	s_bitcmp1_b32 s38, 1
	s_cbranch_scc1 .Lcv_keep
	s_bitcmp1_b32 s38, 2
	s_cbranch_scc1 .Lcv_keep
	s_lshr_b32 s32, s38, 3
	s_and_b32 s0, s92, 7
	s_sub_u32 s0, 7, s0
	s_mul_i32 s0, s0, s32
	s_add_u32 s19, s0, s32
	s_lshr_b32 s1, s92, 3
	s_lshl_b32 s1, s1, 9
	s_add_u32 s0, s0, s1
	s_mov_b32 s1, 0
	s_movk_i32 s32, 0x4000
.Lcv_keep:
	v_ashrrev_i32_e32 v1, 31, v0
	s_mov_b32 s39, s3
	v_lshl_add_u64 v[120:121], s[0:1], 0, v[0:1]
	v_cmp_gt_u32_e32 vcc, s19, v120
	s_and_saveexec_b64 s[8:9], vcc
	s_cbranch_execz .LBB0_766
	v_readlane_b32 s0, v240, 24
	s_mov_b32 s6, s0
	s_mul_i32 s0, s0, 0x18c00
	s_add_u32 s72, s52, s0
	s_addc_u32 s73, s53, 0
	s_mul_i32 s0, s6, 0x2c00
	s_add_u32 s74, s54, s0
	s_addc_u32 s75, s55, 0
	s_mov_b64 s[78:79], 0
	v_readlane_b32 s1, v240, 25
	s_branch .LBB0_702
.LBB0_701:
	s_mov_b32 s0, s32
	s_mov_b32 s1, 0
	s_nop 1
	v_lshl_add_u64 v[120:121], v[120:121], 0, s[0:1]
	v_cmp_le_u32_e32 vcc, s19, v120
	s_or_b64 s[78:79], vcc, s[78:79]
	s_andn2_b64 exec, exec, s[78:79]
	s_cbranch_execz .LBB0_766
